# retention fast-path decay: exp and per-key-tile scalar factors computed in the QK-tail MFMA gaps, 7 VALU and one transcendental latency off the serial chain
# speedup vs baseline: 1.0103x; 1.0103x over previous
.LBB0_865:
	s_and_b32 s49, s48, 1
	s_cmp_gt_i32 s45, s16
	s_cbranch_scc1 .Lt_skipdma
	s_mul_i32 s4, s49, 0x8400
	v_add_u32_e32 v8, s4, v195
	v_xor_b32_e32 v246, 64, v8
	v_xor_b32_e32 v247, 0x80, v8
	v_xor_b32_e32 v248, 0xc0, v8
	ds_read_b128 v[0:3], v8
	ds_read_b128 v[4:7], v8 offset:8192
	ds_read_b128 v[174:177], v8 offset:16384
	ds_read_b128 v[198:201], v8 offset:24576
	ds_read_b128 v[202:205], v246
	ds_read_b128 v[206:209], v246 offset:8192
	ds_read_b128 v[210:213], v246 offset:16384
	ds_read_b128 v[214:217], v246 offset:24576
	ds_read_b128 v[218:221], v247
	ds_read_b128 v[226:229], v247 offset:8192
	ds_read_b128 v[230:233], v247 offset:16384
	ds_read_b128 v[234:237], v247 offset:24576
	ds_read_b128 v[238:241], v248
	ds_read_b128 v[242:245], v248 offset:8192
	s_mul_i32 s5, s49, 0x8800
	v_add_u32_e32 v115, s5, v173
	v_xor_b32_e32 v108, 0x20, v115
	v_xor_b32_e32 v109, 0x40, v115
	v_xor_b32_e32 v110, 0x60, v115
	v_xor_b32_e32 v111, 0x80, v115
	v_xor_b32_e32 v112, 0xa0, v115
	v_xor_b32_e32 v113, 0xc0, v115
	v_xor_b32_e32 v114, 0xe0, v115
	s_add_i32 s4, s45, 63
	s_cmp_le_u32 s4, s9
	s_waitcnt lgkmcnt(13)
	v_mfma_f32_16x16x32_bf16 v[150:153], v[0:3], v[102:105], 0
	ds_read_b128 v[0:3], v248 offset:16384
	s_waitcnt lgkmcnt(13)
	v_mfma_f32_16x16x32_bf16 v[146:149], v[4:7], v[102:105], 0
	ds_read_b128 v[4:7], v248 offset:24576
	s_waitcnt lgkmcnt(13)
	v_mfma_f32_16x16x32_bf16 v[142:145], v[174:177], v[102:105], 0
	ds_read_b128 v[174:177], v8 offset:256
	s_waitcnt lgkmcnt(13)
	v_mfma_f32_16x16x32_bf16 v[138:141], v[198:201], v[102:105], 0
	ds_read_b128 v[198:201], v8 offset:8448
	s_waitcnt lgkmcnt(13)
	v_mfma_f32_16x16x32_bf16 v[150:153], v[202:205], v[98:101], v[150:153]
	ds_read_b128 v[202:205], v8 offset:16640
	s_waitcnt lgkmcnt(13)
	v_mfma_f32_16x16x32_bf16 v[146:149], v[206:209], v[98:101], v[146:149]
	ds_read_b128 v[206:209], v8 offset:24832
	s_waitcnt lgkmcnt(13)
	v_mfma_f32_16x16x32_bf16 v[142:145], v[210:213], v[98:101], v[142:145]
	ds_read_b128 v[210:213], v246 offset:256
	s_waitcnt lgkmcnt(13)
	v_mfma_f32_16x16x32_bf16 v[138:141], v[214:217], v[98:101], v[138:141]
	ds_read_b128 v[214:217], v246 offset:8448
	s_waitcnt lgkmcnt(13)
	v_mfma_f32_16x16x32_bf16 v[150:153], v[218:221], v[94:97], v[150:153]
	ds_read_b128 v[218:221], v246 offset:16640
	s_waitcnt lgkmcnt(13)
	v_mfma_f32_16x16x32_bf16 v[146:149], v[226:229], v[94:97], v[146:149]
	ds_read_b128 v[226:229], v246 offset:24832
	s_waitcnt lgkmcnt(13)
	v_mfma_f32_16x16x32_bf16 v[142:145], v[230:233], v[94:97], v[142:145]
	ds_read_b128 v[230:233], v247 offset:256
	s_waitcnt lgkmcnt(13)
	v_mfma_f32_16x16x32_bf16 v[138:141], v[234:237], v[94:97], v[138:141]
	ds_read_b128 v[234:237], v247 offset:8448
	s_waitcnt lgkmcnt(13)
	v_mfma_f32_16x16x32_bf16 v[150:153], v[238:241], v[90:93], v[150:153]
	ds_read_b128 v[238:241], v247 offset:16640
	s_waitcnt lgkmcnt(13)
	v_mfma_f32_16x16x32_bf16 v[146:149], v[242:245], v[90:93], v[146:149]
	ds_read_b128 v[242:245], v247 offset:24832
	s_waitcnt lgkmcnt(13)
	v_mfma_f32_16x16x32_bf16 v[142:145], v[0:3], v[90:93], v[142:145]
	ds_read_b128 v[0:3], v248 offset:256
	s_waitcnt lgkmcnt(13)
	v_mfma_f32_16x16x32_bf16 v[138:141], v[4:7], v[90:93], v[138:141]
	ds_read_b128 v[4:7], v248 offset:8448
	s_waitcnt lgkmcnt(13)
	v_mfma_f32_16x16x32_bf16 v[150:153], v[174:177], v[86:89], v[150:153]
	ds_read_b128 v[174:177], v248 offset:16640
	s_waitcnt lgkmcnt(13)
	v_mfma_f32_16x16x32_bf16 v[146:149], v[198:201], v[86:89], v[146:149]
	ds_read_b128 v[198:201], v248 offset:24832
	s_waitcnt lgkmcnt(13)
	v_mfma_f32_16x16x32_bf16 v[142:145], v[202:205], v[86:89], v[142:145]
	ds_read_b64_tr_b16 v[116:117], v115
	ds_read_b64_tr_b16 v[118:119], v115 offset:8192
	s_waitcnt lgkmcnt(14)
	v_mfma_f32_16x16x32_bf16 v[138:141], v[206:209], v[86:89], v[138:141]
	ds_read_b64_tr_b16 v[120:121], v108
	v_cvt_f32_i32_e32 v133, v196
	s_waitcnt lgkmcnt(14)
	v_mfma_f32_16x16x32_bf16 v[150:153], v[210:213], v[82:85], v[150:153]
	ds_read_b64_tr_b16 v[122:123], v108 offset:8192
	v_mul_f32_e32 v133, v178, v133
	s_waitcnt lgkmcnt(14)
	v_mfma_f32_16x16x32_bf16 v[146:149], v[214:217], v[82:85], v[146:149]
	ds_read_b64_tr_b16 v[124:125], v109
	v_exp_f32_e32 v133, v133
	s_waitcnt lgkmcnt(14)
	v_mfma_f32_16x16x32_bf16 v[142:145], v[218:221], v[82:85], v[142:145]
	ds_read_b64_tr_b16 v[126:127], v109 offset:8192
	s_waitcnt lgkmcnt(14)
	v_mfma_f32_16x16x32_bf16 v[138:141], v[226:229], v[82:85], v[138:141]
	ds_read_b64_tr_b16 v[128:129], v110
	v_mul_f32_e32 v132, s40, v133
	s_waitcnt lgkmcnt(14)
	v_mfma_f32_16x16x32_bf16 v[150:153], v[230:233], v[78:81], v[150:153]
	ds_read_b64_tr_b16 v[130:131], v110 offset:8192
	v_mul_f32_e32 v134, s44, v133
	s_waitcnt lgkmcnt(14)
	v_mfma_f32_16x16x32_bf16 v[146:149], v[234:237], v[78:81], v[146:149]
	ds_read_b64_tr_b16 v[210:211], v111
	v_mul_f32_e32 v136, s37, v133
	s_waitcnt lgkmcnt(14)
	v_mfma_f32_16x16x32_bf16 v[142:145], v[238:241], v[78:81], v[142:145]
	ds_read_b64_tr_b16 v[212:213], v111 offset:8192
	v_mul_f32_e32 v246, s36, v133
	s_waitcnt lgkmcnt(14)
	v_mfma_f32_16x16x32_bf16 v[138:141], v[242:245], v[78:81], v[138:141]
	ds_read_b64_tr_b16 v[202:203], v112
	s_waitcnt lgkmcnt(14)
	v_mfma_f32_16x16x32_bf16 v[150:153], v[0:3], v[74:77], v[150:153]
	ds_read_b64_tr_b16 v[204:205], v112 offset:8192
	s_waitcnt lgkmcnt(14)
	v_mfma_f32_16x16x32_bf16 v[146:149], v[4:7], v[74:77], v[146:149]
	ds_read_b64_tr_b16 v[206:207], v113
	s_waitcnt lgkmcnt(14)
	v_mfma_f32_16x16x32_bf16 v[142:145], v[174:177], v[74:77], v[142:145]
	ds_read_b64_tr_b16 v[208:209], v113 offset:8192
	s_waitcnt lgkmcnt(14)
	v_mfma_f32_16x16x32_bf16 v[138:141], v[198:201], v[74:77], v[138:141]
	s_lshl_b32 s4, s45, 14
	s_add_i32 s4, s4, 0x100000
	v_readlane_b32 s5, v254, 60
	s_lshl_b32 s5, s5, 10
	s_cmp_eq_u32 s49, 0
	s_cselect_b32 m0, 0x8400, 0
	s_add_i32 m0, m0, s5
	v_add_u32_e32 v0, s4, v106
	v_add_u32_e32 v4, s4, v107
	global_load_lds_dwordx4 v0, s[24:25]
	s_add_i32 m0, m0, 0x2000
	s_add_i32 s4, s4, 0x40000
	v_add_u32_e32 v1, s4, v106
	v_add_u32_e32 v5, s4, v107
	global_load_lds_dwordx4 v1, s[24:25]
	s_add_i32 m0, m0, 0x2000
	s_add_i32 s4, s4, 0x40000
	v_add_u32_e32 v2, s4, v106
	v_add_u32_e32 v6, s4, v107
	global_load_lds_dwordx4 v2, s[24:25]
	s_add_i32 m0, m0, 0x2000
	s_add_i32 s4, s4, 0x40000
	v_add_u32_e32 v3, s4, v106
	v_add_u32_e32 v7, s4, v107
	global_load_lds_dwordx4 v3, s[24:25]
	s_cmp_eq_u32 s49, 0
	s_cselect_b32 m0, 0x8800, 0
	s_add_i32 m0, m0, s5
	s_add_i32 m0, m0, 0x10800
	s_nop 0
	global_load_lds_dwordx4 v4, s[26:27]
	s_add_i32 m0, m0, 0x2000
	s_nop 0
	global_load_lds_dwordx4 v5, s[26:27]
	s_add_i32 m0, m0, 0x2000
	s_nop 0
	global_load_lds_dwordx4 v6, s[26:27]
	s_add_i32 m0, m0, 0x2000
	s_nop 0
	global_load_lds_dwordx4 v7, s[26:27]
	s_add_i32 s4, s45, 63
	s_cmp_le_u32 s4, s9
	s_mov_b64 s[4:5], -1
	s_cbranch_scc0 .LBB0_868
	s_mov_b64 s[4:5], 0
	v_pk_mul_f32 v[2:3], s[40:41], v[132:133] op_sel_hi:[1,0]
	v_pk_mul_f32 v[0:1], s[42:43], v[132:133] op_sel_hi:[1,0]
	v_pk_mul_f32 v[2:3], v[2:3], v[150:151]
	v_pk_mul_f32 v[4:5], v[0:1], v[152:153]
	v_cvt_pk_bf16_f32 v0, v2, v3
	v_cvt_pk_bf16_f32 v1, v4, v5
	v_pk_mul_f32 v[4:5], s[40:41], v[134:135] op_sel_hi:[1,0]
	v_pk_mul_f32 v[2:3], s[42:43], v[134:135] op_sel_hi:[1,0]
	v_pk_mul_f32 v[4:5], v[4:5], v[146:147]
	v_pk_mul_f32 v[6:7], v[2:3], v[148:149]
	v_cvt_pk_bf16_f32 v2, v4, v5
	v_cvt_pk_bf16_f32 v3, v6, v7
	v_pk_mul_f32 v[6:7], s[40:41], v[136:137] op_sel_hi:[1,0]
	v_pk_mul_f32 v[4:5], s[42:43], v[136:137] op_sel_hi:[1,0]
	v_pk_mul_f32 v[6:7], v[6:7], v[142:143]
	v_pk_mul_f32 v[154:155], v[4:5], v[144:145]
	v_cvt_pk_bf16_f32 v4, v6, v7
	v_cvt_pk_bf16_f32 v5, v154, v155
	v_pk_mul_f32 v[154:155], s[40:41], v[246:247] op_sel_hi:[1,0]
	v_pk_mul_f32 v[6:7], s[42:43], v[246:247] op_sel_hi:[1,0]
	v_pk_mul_f32 v[174:175], v[154:155], v[138:139]
	v_pk_mul_f32 v[176:177], v[6:7], v[140:141]
